# grid barrier: one extra early buffer_wbl2 per XCD per seam, issued by the WG arriving at index n/2
# speedup vs baseline: 1.0052x; 1.0007x over previous
.LBB0_1163:
	s_or_b64 exec, exec, s[4:5]
	v_cvt_f32_u32_e32 v4, v2
	s_waitcnt vmcnt(0)
	v_readfirstlane_b32 s2, v3
	v_sub_u32_e32 v3, 0, v2
	v_rcp_iflag_f32_e32 v4, v4
	v_add_u32_e32 v5, s2, v1
	v_mul_f32_e32 v4, 0x4f7ffffe, v4
	v_cvt_u32_f32_e32 v4, v4
	v_mul_lo_u32 v1, v3, v4
	v_mul_hi_u32 v1, v4, v1
	v_add_u32_e32 v1, v4, v1
	v_mul_hi_u32 v1, v5, v1
	v_mul_lo_u32 v3, v1, v2
	v_sub_u32_e32 v3, v5, v3
	v_add_u32_e32 v4, 1, v1
	v_cmp_ge_u32_e32 vcc, v3, v2
	s_nop 1
	v_cndmask_b32_e32 v1, v1, v4, vcc
	v_sub_u32_e32 v4, v3, v2
	v_cndmask_b32_e32 v3, v3, v4, vcc
	v_add_u32_e32 v4, 1, v1
	v_cmp_ge_u32_e32 vcc, v3, v2
	v_add_u32_e32 v3, 1, v5
	s_nop 0
	v_cndmask_b32_e32 v1, v1, v4, vcc
	v_mul_lo_u32 v4, v2, v1
	v_add_u32_e32 v2, v4, v2
	v_cmp_ne_u32_e32 vcc, v3, v2
	s_and_saveexec_b64 s[4:5], vcc
	s_xor_b64 s[4:5], exec, s[4:5]
	s_cbranch_execz .LBB0_1177
	v_sub_u32_e32 v0, v2, v4
	v_lshrrev_b32_e32 v0, 1, v0
	v_sub_u32_e32 v3, v5, v4
	v_cmp_eq_u32_e32 vcc, v3, v0
	s_and_saveexec_b64 s[6:7], vcc
	s_cbranch_execz .Lxb_nowb
	buffer_wbl2 sc1
.Lxb_nowb:
	s_or_b64 exec, exec, s[6:7]
	v_readlane_b32 s6, v255, 19
	v_readlane_b32 s7, v255, 20
	s_waitcnt lgkmcnt(0)
	s_nop 3
	global_load_dword v0, v173, s[6:7] sc1
	s_waitcnt vmcnt(0)
	v_cmp_eq_u32_e32 vcc, v0, v1
	s_and_saveexec_b64 s[6:7], vcc
	s_cbranch_execz .LBB0_1176
	s_mov_b32 s2, 1
	s_mov_b64 s[8:9], 0
	s_branch .LBB0_1167
